# conversion split plus FF1 and FF2 half-skew removed (equal work per workgroup there)
# speedup vs baseline: 1.0004x; 1.0004x over previous
.LBB0_1059:
	s_or_b64 exec, exec, s[4:5]
	s_waitcnt lgkmcnt(0)
	v_mov_b32_e32 v1, v0
	s_mov_b64 s[0:1], s[88:89]
	s_barrier
	s_load_dwordx2 s[4:5], s[0:1], 0x108
	s_and_b64 vcc, exec, s[64:65]
	s_cbranch_vccz .LBB0_1063
	s_memrealtime s[0:1]
	s_memrealtime s[2:3]
	v_mov_b64_e32 v[2:3], 0x0
	s_waitcnt lgkmcnt(0)
	s_sub_u32 s2, s2, s0
	s_subb_u32 s3, s3, s1
	v_cmp_gt_u64_e32 vcc, s[2:3], v[2:3]
	s_cbranch_vccnz .LBB0_1063
	v_mov_b64_e32 v[2:3], 0x0

.LBB0_1132:
	s_or_b64 exec, exec, s[4:5]
	s_waitcnt lgkmcnt(0)
	v_mov_b32_e32 v1, v0
	s_mov_b64 s[0:1], s[88:89]
	s_barrier
	s_load_dwordx2 s[22:23], s[0:1], 0xe0
	s_load_dwordx2 s[12:13], s[0:1], 0x108
	s_and_b64 vcc, exec, s[64:65]
	s_cbranch_vccz .LBB0_1136
	s_memrealtime s[0:1]
	s_memrealtime s[2:3]
	v_mov_b64_e32 v[2:3], 0x0
	s_waitcnt lgkmcnt(0)
	s_sub_u32 s2, s2, s0
	s_subb_u32 s3, s3, s1
	v_cmp_gt_u64_e32 vcc, s[2:3], v[2:3]
	s_cbranch_vccnz .LBB0_1136
	v_mov_b64_e32 v[2:3], 0x0
